# v93 + diff row-sum chains: s_nop pads of the former packed adds removed (3 per stage)
# speedup vs baseline: 1.0026x; 1.0026x over previous
; __device__ __forceinline__ unsigned cvtpk(float lo, float hi) { f32x2 v = {lo, hi}; bf16x2_t b = __builtin_convertvector(v, bf16x2_t); return __builtin_bit_cast(unsigned, b); }
; #define LAS __attribute__((address_space(3)))
; template <int MODE, int NDG> ...
;     ...
;         float s0 = 0.f, s1 = 0.f;
; #pragma unroll
;         for (int r = 0; r < 16; ++r) { p0[r] = __builtin_amdgcn_exp2f(p0[r]); p1[r] = __builtin_amdgcn_exp2f(p1[r]); s0 += p0[r]; s1 += p1[r]; }
;         l += s0 + s1;
;         pw[0] = (u32x4){cvtpk(p0[0], p0[1]), cvtpk(p0[2], p0[3]), cvtpk(p0[4], p0[5]), cvtpk(p0[6], p0[7])};
;         pw[1] = (u32x4){cvtpk(p0[8], p0[9]), cvtpk(p0[10], p0[11]), cvtpk(p0[12], p0[13]), cvtpk(p0[14], p0[15])};
;         pw[2] = (u32x4){cvtpk(p1[0], p1[1]), cvtpk(p1[2], p1[3]), cvtpk(p1[4], p1[5]), cvtpk(p1[6], p1[7])};
;         pw[3] = (u32x4){cvtpk(p1[8], p1[9]), cvtpk(p1[10], p1[11]), cvtpk(p1[12], p1[13]), cvtpk(p1[14], p1[15])};
;     }
;     LAS const unsigned char* vp = vst + ((lane >> 4) & 1) * 32 + (lane & 3) * 8 + (4 * hi + ((lane & 15) >> 2)) * 64;
; #pragma unroll
;     for (int ks = 0; ks < 4; ++ks)
; #pragma unroll
;         for (int dg = 0; dg < NDG; ++dg) {
;             const bf16x8 vf = vfrag(vp + dg * 4096 + ks * 1024);
;             o[dg] = __builtin_amdgcn_mfma_f32_32x32x16_bf16(vf, __builtin_bit_cast(bf16x8, pw[ks]), o[dg], 0, 0, 0);
;         }
.LBB0_197:
	v_add3_u32 v0, s54, v212, v181
	v_add3_u32 v194, v0, v213, v214
	v_exp_f32_e32 v1, v112
	v_exp_f32_e32 v5, v113
	v_exp_f32_e32 v7, v114
	v_exp_f32_e32 v9, v115
	v_exp_f32_e32 v11, v116
	v_exp_f32_e32 v13, v117
	ds_read_b64_tr_b16 v[114:115], v194 offset:53248
	ds_read_b64_tr_b16 v[116:117], v194 offset:53760
	v_exp_f32_e32 v113, v118
	v_exp_f32_e32 v15, v119
	v_cvt_pk_bf16_f32 v224, v1, v5
	v_cvt_pk_bf16_f32 v225, v7, v9
	v_cvt_pk_bf16_f32 v226, v11, v13
	v_cvt_pk_bf16_f32 v227, v113, v15
	ds_read_b64_tr_b16 v[228:229], v194 offset:54272
	ds_read_b64_tr_b16 v[230:231], v194 offset:54784
	s_waitcnt lgkmcnt(2)
	v_mfma_f32_32x32x16_bf16 v[64:79], v[114:117], v[224:227], v[64:79]
	ds_read_b64_tr_b16 v[114:115], v194 offset:57344
	ds_read_b64_tr_b16 v[116:117], v194 offset:57856
	ds_read_b64_tr_b16 v[232:233], v194 offset:58368
	ds_read_b64_tr_b16 v[234:235], v194 offset:58880
	v_add_u32_e32 v198, 0xd000, v194
	v_exp_f32_e32 v195, v120
	v_exp_f32_e32 v121, v121
	v_exp_f32_e32 v119, v122
	v_exp_f32_e32 v203, v125
	v_exp_f32_e32 v125, v126
	s_waitcnt lgkmcnt(2)
	v_mfma_f32_32x32x16_bf16 v[48:63], v[114:117], v[224:227], v[48:63]
	ds_read_b64_tr_b16 v[114:115], v194 offset:61440
	ds_read_b64_tr_b16 v[116:117], v194 offset:61952
	ds_read_b64_tr_b16 v[236:237], v198 offset:12288
	ds_read_b64_tr_b16 v[238:239], v198 offset:12800
	ds_read_b64_tr_b16 v[240:241], v194 offset:62464
	ds_read_b64_tr_b16 v[242:243], v194 offset:62976
	ds_read_b64_tr_b16 v[244:245], v198 offset:13312
	ds_read_b64_tr_b16 v[246:247], v198 offset:13824
	v_exp_f32_e32 v0, v96
	v_exp_f32_e32 v4, v97
	v_exp_f32_e32 v6, v98
	v_exp_f32_e32 v8, v99
	s_waitcnt lgkmcnt(6)
	v_mfma_f32_32x32x16_bf16 v[32:47], v[114:117], v[224:227], v[32:47]
	v_exp_f32_e32 v117, v123
	v_exp_f32_e32 v115, v124
	v_exp_f32_e32 v123, v127
	v_exp_f32_e32 v10, v100
	v_exp_f32_e32 v12, v101
	v_exp_f32_e32 v112, v102
	ds_read_b64_tr_b16 v[96:97], v194 offset:55296
	ds_read_b64_tr_b16 v[98:99], v194 offset:55808
	s_waitcnt lgkmcnt(6)
	v_mfma_f32_32x32x16_bf16 v[16:31], v[236:239], v[224:227], v[16:31]
	v_cvt_pk_bf16_f32 v224, v195, v121
	v_cvt_pk_bf16_f32 v225, v119, v117
	v_cvt_pk_bf16_f32 v226, v115, v203
	v_cvt_pk_bf16_f32 v227, v125, v123
	v_exp_f32_e32 v14, v103
	v_cvt_pk_bf16_f32 v100, v0, v4
	v_cvt_pk_bf16_f32 v101, v6, v8
	v_mfma_f32_32x32x16_bf16 v[64:79], v[228:231], v[224:227], v[64:79]
	v_cvt_pk_bf16_f32 v102, v10, v12
	v_cvt_pk_bf16_f32 v103, v112, v14
	v_add_f32_e64 v0, v0, 0
	v_add_f32_e64 v1, v1, 0
	v_exp_f32_e32 v120, v105
	v_add_f32_e32 v0, v4, v0
	v_add_f32_e32 v1, v5, v1
	v_exp_f32_e32 v118, v106
	v_add_f32_e32 v0, v6, v0
	v_add_f32_e32 v1, v7, v1
	v_mfma_f32_32x32x16_bf16 v[48:63], v[232:235], v[224:227], v[48:63]
	v_add_f32_e64 v0, v8, v0
	v_add_f32_e64 v1, v9, v1
	v_exp_f32_e32 v116, v107
	v_add_f32_e32 v0, v10, v0
	v_add_f32_e32 v1, v11, v1
	v_exp_f32_e32 v114, v108
	v_exp_f32_e32 v202, v109
	v_exp_f32_e32 v124, v110
	v_exp_f32_e32 v122, v111
	s_waitcnt lgkmcnt(4)
	v_mfma_f32_32x32x16_bf16 v[32:47], v[240:243], v[224:227], v[32:47]
	v_add_f32_e64 v0, v12, v0
	v_add_f32_e64 v1, v13, v1
	v_add_f32_e64 v0, v112, v0
	v_add_f32_e64 v1, v113, v1
	v_add_f32_e64 v0, v14, v0
	v_add_f32_e64 v1, v15, v1
	s_waitcnt lgkmcnt(2)
	v_mfma_f32_32x32x16_bf16 v[16:31], v[244:247], v[224:227], v[16:31]
	ds_read_b64_tr_b16 v[224:225], v194 offset:56320
	ds_read_b64_tr_b16 v[226:227], v194 offset:56832
	s_waitcnt lgkmcnt(2)
	v_mfma_f32_32x32x16_bf16 v[64:79], v[96:99], v[100:103], v[64:79]
	ds_read_b64_tr_b16 v[96:97], v194 offset:59392
	ds_read_b64_tr_b16 v[98:99], v194 offset:59904
	ds_read_b64_tr_b16 v[228:229], v194 offset:60416
	ds_read_b64_tr_b16 v[230:231], v194 offset:60928
	s_waitcnt lgkmcnt(2)
	v_mfma_f32_32x32x16_bf16 v[48:63], v[96:99], v[100:103], v[48:63]
	ds_read_b64_tr_b16 v[96:97], v194 offset:63488
	ds_read_b64_tr_b16 v[98:99], v194 offset:64000
	ds_read_b64_tr_b16 v[232:233], v198 offset:14336
	ds_read_b64_tr_b16 v[234:235], v198 offset:14848
	ds_read_b64_tr_b16 v[236:237], v194 offset:64512
	ds_read_b64_tr_b16 v[238:239], v194 offset:65024
	v_exp_f32_e32 v194, v104
	v_add_f32_e32 v1, v195, v1
	v_add_f32_e32 v0, v194, v0
	v_add_f32_e32 v0, v120, v0
	v_add_f32_e32 v1, v121, v1
	s_waitcnt lgkmcnt(4)
	v_mfma_f32_32x32x16_bf16 v[32:47], v[96:99], v[100:103], v[32:47]
	ds_read_b64_tr_b16 v[96:97], v198 offset:15360
	ds_read_b64_tr_b16 v[98:99], v198 offset:15872
	v_add_f32_e64 v0, v118, v0
	v_add_f32_e64 v1, v119, v1
	v_add_f32_e64 v0, v116, v0
	v_add_f32_e64 v1, v117, v1
	v_add_f32_e32 v0, v114, v0
	v_add_f32_e32 v1, v115, v1
	s_waitcnt lgkmcnt(4)
	v_mfma_f32_32x32x16_bf16 v[16:31], v[232:235], v[100:103], v[16:31]
	v_cvt_pk_bf16_f32 v100, v194, v120
	v_cvt_pk_bf16_f32 v101, v118, v116
	v_cvt_pk_bf16_f32 v102, v114, v202
	v_cvt_pk_bf16_f32 v103, v124, v122
	v_add_f32_e64 v0, v202, v0
	v_add_f32_e64 v1, v203, v1
	v_add_f32_e32 v0, v124, v0
	v_add_f32_e32 v1, v125, v1
	v_mfma_f32_32x32x16_bf16 v[64:79], v[224:227], v[100:103], v[64:79]
	v_add_f32_e64 v0, v122, v0
	v_add_f32_e64 v1, v123, v1
	v_add_f32_e32 v0, v0, v1
	v_add_f32_e32 v3, v3, v0
	v_mfma_f32_32x32x16_bf16 v[48:63], v[228:231], v[100:103], v[48:63]
	s_waitcnt lgkmcnt(2)
	v_mfma_f32_32x32x16_bf16 v[32:47], v[236:239], v[100:103], v[32:47]
	s_waitcnt lgkmcnt(0)
	v_mfma_f32_32x32x16_bf16 v[16:31], v[96:99], v[100:103], v[16:31]
	s_cmp_gt_u32 s50, s48
	s_cbranch_scc1 .LBB0_190

; __device__ __forceinline__ unsigned cvtpk(float lo, float hi) { f32x2 v = {lo, hi}; bf16x2_t b = __builtin_convertvector(v, bf16x2_t); return __builtin_bit_cast(unsigned, b); }
; #define LAS __attribute__((address_space(3)))
; template <int MODE, int NDG> ...
;     ...
;         float s0 = 0.f, s1 = 0.f;
; #pragma unroll
;         for (int r = 0; r < 16; ++r) { p0[r] = __builtin_amdgcn_exp2f(p0[r]); p1[r] = __builtin_amdgcn_exp2f(p1[r]); s0 += p0[r]; s1 += p1[r]; }
;         l += s0 + s1;
;         pw[0] = (u32x4){cvtpk(p0[0], p0[1]), cvtpk(p0[2], p0[3]), cvtpk(p0[4], p0[5]), cvtpk(p0[6], p0[7])};
;         pw[1] = (u32x4){cvtpk(p0[8], p0[9]), cvtpk(p0[10], p0[11]), cvtpk(p0[12], p0[13]), cvtpk(p0[14], p0[15])};
;         pw[2] = (u32x4){cvtpk(p1[0], p1[1]), cvtpk(p1[2], p1[3]), cvtpk(p1[4], p1[5]), cvtpk(p1[6], p1[7])};
;         pw[3] = (u32x4){cvtpk(p1[8], p1[9]), cvtpk(p1[10], p1[11]), cvtpk(p1[12], p1[13]), cvtpk(p1[14], p1[15])};
;     }
;     LAS const unsigned char* vp = vst + ((lane >> 4) & 1) * 32 + (lane & 3) * 8 + (4 * hi + ((lane & 15) >> 2)) * 64;
; #pragma unroll
;     for (int ks = 0; ks < 4; ++ks)
; #pragma unroll
;         for (int dg = 0; dg < NDG; ++dg) {
;             const bf16x8 vf = vfrag(vp + dg * 4096 + ks * 1024);
;             o[dg] = __builtin_amdgcn_mfma_f32_32x32x16_bf16(vf, __builtin_bit_cast(bf16x8, pw[ks]), o[dg], 0, 0, 0);
;         }
.LBB0_204:
	v_add3_u32 v0, s54, v212, v181
	v_add3_u32 v198, v0, v213, v214
	v_exp_f32_e32 v1, v112
	v_exp_f32_e32 v5, v113
	v_exp_f32_e32 v7, v114
	v_exp_f32_e32 v9, v115
	v_exp_f32_e32 v11, v116
	v_exp_f32_e32 v13, v117
	ds_read_b64_tr_b16 v[114:115], v198 offset:36864
	ds_read_b64_tr_b16 v[116:117], v198 offset:37376
	v_exp_f32_e32 v113, v118
	v_exp_f32_e32 v15, v119
	v_cvt_pk_bf16_f32 v222, v1, v5
	v_cvt_pk_bf16_f32 v223, v7, v9
	v_cvt_pk_bf16_f32 v224, v11, v13
	v_cvt_pk_bf16_f32 v225, v113, v15
	ds_read_b64_tr_b16 v[226:227], v198 offset:37888
	ds_read_b64_tr_b16 v[228:229], v198 offset:38400
	s_waitcnt lgkmcnt(2)
	v_mfma_f32_32x32x16_bf16 v[64:79], v[114:117], v[222:225], v[64:79]
	ds_read_b64_tr_b16 v[114:115], v198 offset:40960
	ds_read_b64_tr_b16 v[116:117], v198 offset:41472
	ds_read_b64_tr_b16 v[230:231], v198 offset:41984
	ds_read_b64_tr_b16 v[232:233], v198 offset:42496
	v_exp_f32_e32 v195, v120
	v_exp_f32_e32 v121, v121
	v_exp_f32_e32 v119, v122
	v_exp_f32_e32 v203, v125
	v_exp_f32_e32 v125, v126
	v_exp_f32_e32 v0, v96
	s_waitcnt lgkmcnt(2)
	v_mfma_f32_32x32x16_bf16 v[48:63], v[114:117], v[222:225], v[48:63]
	ds_read_b64_tr_b16 v[114:115], v198 offset:45056
	ds_read_b64_tr_b16 v[116:117], v198 offset:45568
	ds_read_b64_tr_b16 v[234:235], v198 offset:49152
	ds_read_b64_tr_b16 v[236:237], v198 offset:49664
	ds_read_b64_tr_b16 v[238:239], v198 offset:46080
	ds_read_b64_tr_b16 v[240:241], v198 offset:46592
	ds_read_b64_tr_b16 v[242:243], v198 offset:50176
	ds_read_b64_tr_b16 v[244:245], v198 offset:50688
	v_exp_f32_e32 v4, v97
	v_exp_f32_e32 v6, v98
	v_exp_f32_e32 v8, v99
	v_exp_f32_e32 v10, v100
	v_exp_f32_e32 v12, v101
	s_waitcnt lgkmcnt(6)
	v_mfma_f32_32x32x16_bf16 v[32:47], v[114:117], v[222:225], v[32:47]
	v_exp_f32_e32 v117, v123
	v_exp_f32_e32 v115, v124
	v_exp_f32_e32 v123, v127
	v_exp_f32_e32 v112, v102
	ds_read_b64_tr_b16 v[96:97], v198 offset:38912
	ds_read_b64_tr_b16 v[98:99], v198 offset:39424
	v_exp_f32_e32 v14, v103
	v_cvt_pk_bf16_f32 v100, v0, v4
	s_waitcnt lgkmcnt(6)
	v_mfma_f32_32x32x16_bf16 v[16:31], v[234:237], v[222:225], v[16:31]
	v_cvt_pk_bf16_f32 v222, v195, v121
	v_cvt_pk_bf16_f32 v223, v119, v117
	v_cvt_pk_bf16_f32 v224, v115, v203
	v_cvt_pk_bf16_f32 v225, v125, v123
	v_cvt_pk_bf16_f32 v101, v6, v8
	v_cvt_pk_bf16_f32 v102, v10, v12
	v_cvt_pk_bf16_f32 v103, v112, v14
	v_mfma_f32_32x32x16_bf16 v[64:79], v[226:229], v[222:225], v[64:79]
	v_add_f32_e64 v0, v0, 0
	v_add_f32_e64 v1, v1, 0
	v_exp_f32_e32 v194, v104
	v_add_f32_e32 v0, v4, v0
	v_add_f32_e32 v1, v5, v1
	v_exp_f32_e32 v120, v105
	v_add_f32_e32 v0, v6, v0
	v_add_f32_e32 v1, v7, v1
	v_exp_f32_e32 v118, v106
	v_add_f32_e32 v0, v8, v0
	v_add_f32_e32 v1, v9, v1
	v_mfma_f32_32x32x16_bf16 v[48:63], v[230:233], v[222:225], v[48:63]
	v_add_f32_e64 v0, v10, v0
	v_add_f32_e64 v1, v11, v1
	v_exp_f32_e32 v116, v107
	v_exp_f32_e32 v114, v108
	v_exp_f32_e32 v202, v109
	v_exp_f32_e32 v124, v110
	v_exp_f32_e32 v122, v111
	v_add_f32_e32 v0, v12, v0
	v_add_f32_e32 v1, v13, v1
	s_waitcnt lgkmcnt(4)
	v_mfma_f32_32x32x16_bf16 v[32:47], v[238:241], v[222:225], v[32:47]
	v_add_f32_e64 v0, v112, v0
	v_add_f32_e64 v1, v113, v1
	v_add_f32_e64 v0, v14, v0
	v_add_f32_e64 v1, v15, v1
	v_add_f32_e64 v0, v194, v0
	v_add_f32_e64 v1, v195, v1
	v_add_f32_e32 v0, v120, v0
	v_add_f32_e32 v1, v121, v1
	s_waitcnt lgkmcnt(2)
	v_mfma_f32_32x32x16_bf16 v[16:31], v[242:245], v[222:225], v[16:31]
	ds_read_b64_tr_b16 v[222:223], v198 offset:39936
	ds_read_b64_tr_b16 v[224:225], v198 offset:40448
	v_add_f32_e64 v0, v118, v0
	v_add_f32_e64 v1, v119, v1
	v_add_f32_e64 v0, v116, v0
	v_add_f32_e64 v1, v117, v1
	v_add_f32_e32 v0, v114, v0
	v_add_f32_e32 v1, v115, v1
	s_waitcnt lgkmcnt(2)
	v_mfma_f32_32x32x16_bf16 v[64:79], v[96:99], v[100:103], v[64:79]
	ds_read_b64_tr_b16 v[96:97], v198 offset:43008
	ds_read_b64_tr_b16 v[98:99], v198 offset:43520
	ds_read_b64_tr_b16 v[226:227], v198 offset:44032
	ds_read_b64_tr_b16 v[228:229], v198 offset:44544
	v_add_f32_e64 v0, v202, v0
	v_add_f32_e64 v1, v203, v1
	v_add_f32_e32 v0, v124, v0
	v_add_f32_e32 v1, v125, v1
	v_add_f32_e32 v0, v122, v0
	v_add_f32_e32 v1, v123, v1
	s_waitcnt lgkmcnt(2)
	v_mfma_f32_32x32x16_bf16 v[48:63], v[96:99], v[100:103], v[48:63]
	ds_read_b64_tr_b16 v[96:97], v198 offset:47104
	ds_read_b64_tr_b16 v[98:99], v198 offset:47616
	ds_read_b64_tr_b16 v[230:231], v198 offset:51200
	ds_read_b64_tr_b16 v[232:233], v198 offset:51712
	ds_read_b64_tr_b16 v[234:235], v198 offset:48128
	ds_read_b64_tr_b16 v[236:237], v198 offset:48640
	v_add_f32_e32 v0, v0, v1
	v_add_f32_e32 v3, v3, v0
	s_waitcnt lgkmcnt(4)
	v_mfma_f32_32x32x16_bf16 v[32:47], v[96:99], v[100:103], v[32:47]
	ds_read_b64_tr_b16 v[96:97], v198 offset:52224
	ds_read_b64_tr_b16 v[98:99], v198 offset:52736
	s_waitcnt lgkmcnt(4)
	v_mfma_f32_32x32x16_bf16 v[16:31], v[230:233], v[100:103], v[16:31]
	v_cvt_pk_bf16_f32 v100, v194, v120
	v_cvt_pk_bf16_f32 v101, v118, v116
	v_cvt_pk_bf16_f32 v102, v114, v202
	v_cvt_pk_bf16_f32 v103, v124, v122
	s_nop 1
	v_mfma_f32_32x32x16_bf16 v[64:79], v[222:225], v[100:103], v[64:79]
	v_mfma_f32_32x32x16_bf16 v[48:63], v[226:229], v[100:103], v[48:63]
	s_waitcnt lgkmcnt(2)
	v_mfma_f32_32x32x16_bf16 v[32:47], v[234:237], v[100:103], v[32:47]
	s_waitcnt lgkmcnt(0)
	v_mfma_f32_32x32x16_bf16 v[16:31], v[96:99], v[100:103], v[16:31]
	s_andn2_b64 vcc, exec, s[30:31]
	s_add_i32 s52, s52, 1
	s_cbranch_vccnz .LBB0_185
